# first grid barrier: the 16 XCD registration words are read with 16 loads in flight instead of 14 dependent round trips per poll
# baseline (speedup 1.0000x reference)
; __device__ __forceinline__ unsigned xb_ld(unsigned* p)              { return __hip_atomic_load(p, __ATOMIC_RELAXED, __HIP_MEMORY_SCOPE_AGENT); }
; __device__ __forceinline__ void xcd_barrier_complete(unsigned* bar, unsigned x, unsigned& nloc, unsigned& nx) {
;     ...
;     for (;;) {
;         sum = 0u; cnt = 0u; mine = 0u;
; #pragma unroll
;         for (unsigned j = 0; j < 16; ++j) { const unsigned c = xb_ld(&bar[XB_XCNT(j)]); sum += c; cnt += (c > 0u) ? 1u : 0u; mine = (j == x) ? c : mine; }
;         if (sum == G) break;
.LBB0_1964:
	v_mov_b64_e32 v[198:199], s[2:3]
	v_mov_b64_e32 v[200:201], s[4:5]
	v_mov_b64_e32 v[202:203], s[6:7]
	v_mov_b64_e32 v[204:205], s[8:9]
	v_mov_b64_e32 v[206:207], s[10:11]
	flat_load_dword v1, v[198:199] offset:1024 sc1
	flat_load_dword v0, v[198:199] offset:1280 sc1
	flat_load_dword v2, v[198:199] offset:1536 sc1
	flat_load_dword v3, v[198:199] offset:1792 sc1
	flat_load_dword v4, v[198:199] offset:2048 sc1
	flat_load_dword v5, v[198:199] offset:2304 sc1
	flat_load_dword v6, v[198:199] offset:2560 sc1
	flat_load_dword v7, v[198:199] offset:2816 sc1
	flat_load_dword v8, v[198:199] offset:3072 sc1
	flat_load_dword v9, v[198:199] offset:3328 sc1
	flat_load_dword v10, v[198:199] offset:3584 sc1
	flat_load_dword v11, v[198:199] offset:3840 sc1
	flat_load_dword v12, v[200:201] sc1
	flat_load_dword v13, v[202:203] sc1
	flat_load_dword v14, v[204:205] sc1
	flat_load_dword v15, v[206:207] sc1
	s_or_b64 s[18:19], s[18:19], exec
	s_or_b64 s[16:17], s[16:17], exec
	s_waitcnt vmcnt(0) lgkmcnt(0)
	v_add_u32_e32 v16, v0, v1
	v_add_u32_e32 v16, v16, v2
	v_add_u32_e32 v16, v16, v3
	v_add_u32_e32 v16, v16, v4
	v_add_u32_e32 v16, v16, v5
	v_add_u32_e32 v16, v16, v6
	v_add_u32_e32 v16, v16, v7
	v_add_u32_e32 v16, v16, v8
	v_add_u32_e32 v16, v16, v9
	v_add_u32_e32 v16, v16, v10
	v_add_u32_e32 v16, v16, v11
	v_add_u32_e32 v16, v16, v12
	v_add_u32_e32 v16, v16, v13
	v_add_u32_e32 v16, v16, v14
	v_add_u32_e32 v16, v16, v15
	v_cmp_ne_u32_e32 vcc, s92, v16
	s_and_saveexec_b64 s[20:21], vcc
	s_cbranch_execz .LBB0_1963
	s_and_b32 s24, s30, 0xff
	s_mov_b64 s[22:23], -1
	s_cmp_eq_u32 s24, 0
	s_mov_b64 s[26:27], -1
	s_mov_b64 s[24:25], -1
	s_sleep 1
	s_cbranch_scc1 .LBB0_1967
	s_and_saveexec_b64 s[28:29], s[26:27]
	s_cbranch_execz .LBB0_1962
	s_branch .LBB0_1970
